# stack + P1 gate-image stores written through (sc1)
# baseline (speedup 1.0000x reference)
.LBB0_135:
	s_add_i32 s6, s90, -10
	v_lshl_or_b32 v138, s6, 8, v181
	v_lshl_add_u64 v[176:177], v[138:139], 2, s[48:49]
	global_load_dwordx4 v[156:159], v[176:177], off offset:16
	global_load_dwordx4 v[160:163], v[176:177], off
	s_lshl_b32 s7, s6, 4
	s_and_b32 s7, s7, 0x3fffffc0
	s_add_i32 s7, s7, s38
	s_lshl_b32 s7, s7, 2
	s_and_b32 s6, s6, 3
	s_or_b32 s6, s7, s6
	s_ashr_i32 s7, s6, 31
	s_lshl_b64 s[6:7], s[6:7], 16
	s_waitcnt vmcnt(0)
	v_pk_mul_f32 v[164:165], v[158:159], s[96:97] op_sel_hi:[1,0]
	v_pk_mul_f32 v[168:169], v[156:157], s[96:97] op_sel_hi:[1,0]
	global_load_dwordx4 v[172:175], v[176:177], off offset:528
	global_load_dwordx4 v[156:159], v[176:177], off offset:512
	v_pk_mul_f32 v[170:171], v[160:161], s[96:97] op_sel_hi:[1,0]
	v_fmamk_f32 v56, v56, 0xbfb8aa3b, v168
	v_fmamk_f32 v120, v120, 0xbfb8aa3b, v168
	v_fmamk_f32 v104, v104, 0xbfb8aa3b, v168
	v_fmamk_f32 v88, v88, 0xbfb8aa3b, v168
	v_fmamk_f32 v72, v72, 0xbfb8aa3b, v168
	v_exp_f32_e32 v56, v56
	v_fmamk_f32 v57, v57, 0xbfb8aa3b, v169
	v_fmamk_f32 v40, v40, 0xbfb8aa3b, v168
	v_fmamk_f32 v24, v24, 0xbfb8aa3b, v168
	v_fmamk_f32 v8, v8, 0xbfb8aa3b, v168
	v_pk_mul_f32 v[166:167], v[162:163], s[96:97] op_sel_hi:[1,0]
	v_exp_f32_e32 v120, v120
	v_fmamk_f32 v121, v121, 0xbfb8aa3b, v169
	v_exp_f32_e32 v104, v104
	v_fmamk_f32 v105, v105, 0xbfb8aa3b, v169
	v_exp_f32_e32 v88, v88
	v_fmamk_f32 v89, v89, 0xbfb8aa3b, v169
	v_exp_f32_e32 v72, v72
	v_fmamk_f32 v73, v73, 0xbfb8aa3b, v169
	v_exp_f32_e32 v57, v57
	v_fmamk_f32 v58, v58, 0xbfb8aa3b, v164
	v_exp_f32_e32 v40, v40
	v_fmamk_f32 v41, v41, 0xbfb8aa3b, v169
	v_exp_f32_e32 v24, v24
	v_fmamk_f32 v25, v25, 0xbfb8aa3b, v169
	v_exp_f32_e32 v8, v8
	v_fmac_f32_e32 v169, 0xbfb8aa3b, v9
	v_exp_f32_e32 v121, v121
	v_fmamk_f32 v122, v122, 0xbfb8aa3b, v164
	v_exp_f32_e32 v105, v105
	v_fmamk_f32 v106, v106, 0xbfb8aa3b, v164
	v_exp_f32_e32 v89, v89
	v_fmamk_f32 v90, v90, 0xbfb8aa3b, v164
	v_exp_f32_e32 v73, v73
	v_fmamk_f32 v74, v74, 0xbfb8aa3b, v164
	v_exp_f32_e32 v58, v58
	v_exp_f32_e32 v41, v41
	v_fmamk_f32 v42, v42, 0xbfb8aa3b, v164
	v_exp_f32_e32 v25, v25
	v_fmamk_f32 v26, v26, 0xbfb8aa3b, v164
	v_exp_f32_e32 v9, v169
	v_exp_f32_e32 v122, v122
	v_exp_f32_e32 v106, v106
	v_exp_f32_e32 v90, v90
	v_exp_f32_e32 v74, v74
	v_exp_f32_e32 v42, v42
	v_exp_f32_e32 v26, v26
	v_fmamk_f32 v10, v10, 0xbfb8aa3b, v164
	v_fmamk_f32 v56, v56, 0x3b808081, v205
	v_exp_f32_e32 v10, v10
	v_fmamk_f32 v120, v120, 0x3b808081, v205
	v_fmamk_f32 v104, v104, 0x3b808081, v205
	v_fmamk_f32 v88, v88, 0x3b808081, v205
	v_fmamk_f32 v72, v72, 0x3b808081, v205
	v_rcp_f32_e32 v56, v56
	v_fmamk_f32 v57, v57, 0x3b808081, v205
	v_fmamk_f32 v40, v40, 0x3b808081, v205
	v_fmamk_f32 v24, v24, 0x3b808081, v205
	v_fmamk_f32 v8, v8, 0x3b808081, v205
	v_rcp_f32_e32 v120, v120
	v_fmamk_f32 v121, v121, 0x3b808081, v205
	v_rcp_f32_e32 v104, v104
	v_fmamk_f32 v105, v105, 0x3b808081, v205
	v_rcp_f32_e32 v88, v88
	v_fmamk_f32 v89, v89, 0x3b808081, v205
	v_rcp_f32_e32 v72, v72
	v_fmamk_f32 v73, v73, 0x3b808081, v205
	v_rcp_f32_e32 v57, v57
	v_fmamk_f32 v58, v58, 0x3b808081, v205
	v_rcp_f32_e32 v40, v40
	v_fmamk_f32 v41, v41, 0x3b808081, v205
	v_rcp_f32_e32 v24, v24
	v_fmamk_f32 v25, v25, 0x3b808081, v205
	v_rcp_f32_e32 v8, v8
	v_fmamk_f32 v9, v9, 0x3b808081, v205
	v_rcp_f32_e32 v121, v121
	v_fmamk_f32 v122, v122, 0x3b808081, v205
	s_waitcnt vmcnt(1)
	v_pk_mul_f32 v[160:161], v[172:173], s[96:97] op_sel_hi:[1,0]
	s_waitcnt vmcnt(0)
	v_pk_mul_f32 v[162:163], v[156:157], s[96:97] op_sel_hi:[1,0]
	v_fmamk_f32 v112, v112, 0xbfb8aa3b, v160
	v_fmamk_f32 v96, v96, 0xbfb8aa3b, v160
	v_fmamk_f32 v80, v80, 0xbfb8aa3b, v160
	v_fmamk_f32 v64, v64, 0xbfb8aa3b, v160
	v_fmamk_f32 v48, v48, 0xbfb8aa3b, v160
	v_fmamk_f32 v32, v32, 0xbfb8aa3b, v160
	v_fmamk_f32 v16, v16, 0xbfb8aa3b, v160
	v_fmamk_f32 v0, v0, 0xbfb8aa3b, v160
	v_pk_mul_f32 v[156:157], v[174:175], s[96:97] op_sel_hi:[1,0]
	v_exp_f32_e32 v112, v112
	v_fmamk_f32 v113, v113, 0xbfb8aa3b, v161
	v_exp_f32_e32 v96, v96
	v_fmamk_f32 v97, v97, 0xbfb8aa3b, v161
	v_exp_f32_e32 v80, v80
	v_fmamk_f32 v81, v81, 0xbfb8aa3b, v161
	v_exp_f32_e32 v64, v64
	v_fmamk_f32 v65, v65, 0xbfb8aa3b, v161
	v_exp_f32_e32 v48, v48
	v_fmamk_f32 v49, v49, 0xbfb8aa3b, v161
	v_exp_f32_e32 v32, v32
	v_fmamk_f32 v33, v33, 0xbfb8aa3b, v161
	v_exp_f32_e32 v16, v16
	v_fmamk_f32 v17, v17, 0xbfb8aa3b, v161
	v_exp_f32_e32 v0, v0
	v_fmac_f32_e32 v161, 0xbfb8aa3b, v1
	v_exp_f32_e32 v113, v113
	v_fmamk_f32 v114, v114, 0xbfb8aa3b, v156
	v_exp_f32_e32 v97, v97
	v_fmamk_f32 v98, v98, 0xbfb8aa3b, v156
	v_exp_f32_e32 v81, v81
	v_fmamk_f32 v82, v82, 0xbfb8aa3b, v156
	v_exp_f32_e32 v65, v65
	v_fmamk_f32 v66, v66, 0xbfb8aa3b, v156
	v_exp_f32_e32 v49, v49
	v_fmamk_f32 v50, v50, 0xbfb8aa3b, v156
	v_exp_f32_e32 v33, v33
	v_fmamk_f32 v34, v34, 0xbfb8aa3b, v156
	v_exp_f32_e32 v17, v17
	v_fmamk_f32 v18, v18, 0xbfb8aa3b, v156
	v_exp_f32_e32 v1, v161
	v_exp_f32_e32 v114, v114
	v_exp_f32_e32 v98, v98
	v_exp_f32_e32 v82, v82
	v_exp_f32_e32 v66, v66
	v_exp_f32_e32 v50, v50
	v_exp_f32_e32 v34, v34
	v_exp_f32_e32 v18, v18
	v_fmamk_f32 v2, v2, 0xbfb8aa3b, v156
	v_exp_f32_e32 v2, v2
	v_fmamk_f32 v112, v112, 0x3b808081, v205
	v_fmamk_f32 v96, v96, 0x3b808081, v205
	v_fmamk_f32 v80, v80, 0x3b808081, v205
	v_fmamk_f32 v64, v64, 0x3b808081, v205
	v_fmamk_f32 v48, v48, 0x3b808081, v205
	v_fmamk_f32 v32, v32, 0x3b808081, v205
	v_fmamk_f32 v16, v16, 0x3b808081, v205
	v_fmamk_f32 v0, v0, 0x3b808081, v205
	v_rcp_f32_e32 v112, v112
	v_fmamk_f32 v113, v113, 0x3b808081, v205
	v_rcp_f32_e32 v96, v96
	v_fmamk_f32 v97, v97, 0x3b808081, v205
	v_rcp_f32_e32 v80, v80
	v_fmamk_f32 v81, v81, 0x3b808081, v205
	v_rcp_f32_e32 v64, v64
	v_fmamk_f32 v65, v65, 0x3b808081, v205
	v_rcp_f32_e32 v48, v48
	v_fmamk_f32 v49, v49, 0x3b808081, v205
	v_rcp_f32_e32 v32, v32
	v_fmamk_f32 v33, v33, 0x3b808081, v205
	v_rcp_f32_e32 v16, v16
	v_fmamk_f32 v17, v17, 0x3b808081, v205
	v_rcp_f32_e32 v0, v0
	v_fmamk_f32 v1, v1, 0x3b808081, v205
	v_rcp_f32_e32 v113, v113
	v_fmamk_f32 v114, v114, 0x3b808081, v205
	v_rcp_f32_e32 v105, v105
	v_fmamk_f32 v106, v106, 0x3b808081, v205
	v_rcp_f32_e32 v97, v97
	v_fmamk_f32 v98, v98, 0x3b808081, v205
	v_rcp_f32_e32 v89, v89
	v_fmamk_f32 v90, v90, 0x3b808081, v205
	v_rcp_f32_e32 v81, v81
	v_fmamk_f32 v82, v82, 0x3b808081, v205
	v_rcp_f32_e32 v73, v73
	v_fmamk_f32 v74, v74, 0x3b808081, v205
	v_rcp_f32_e32 v65, v65
	v_fmamk_f32 v66, v66, 0x3b808081, v205
	v_rcp_f32_e32 v58, v58
	v_rcp_f32_e32 v49, v49
	v_fmamk_f32 v50, v50, 0x3b808081, v205
	v_rcp_f32_e32 v41, v41
	v_fmamk_f32 v42, v42, 0x3b808081, v205
	v_rcp_f32_e32 v33, v33
	v_fmamk_f32 v34, v34, 0x3b808081, v205
	v_rcp_f32_e32 v25, v25
	v_fmamk_f32 v26, v26, 0x3b808081, v205
	v_rcp_f32_e32 v17, v17
	v_fmamk_f32 v18, v18, 0x3b808081, v205
	v_rcp_f32_e32 v9, v9
	v_rcp_f32_e32 v1, v1
	v_rcp_f32_e32 v122, v122
	v_rcp_f32_e32 v114, v114
	v_rcp_f32_e32 v106, v106
	v_rcp_f32_e32 v98, v98
	v_rcp_f32_e32 v90, v90
	v_rcp_f32_e32 v82, v82
	v_rcp_f32_e32 v74, v74
	v_rcp_f32_e32 v66, v66
	v_rcp_f32_e32 v50, v50
	v_rcp_f32_e32 v42, v42
	v_rcp_f32_e32 v34, v34
	v_rcp_f32_e32 v26, v26
	v_rcp_f32_e32 v18, v18
	v_fmamk_f32 v10, v10, 0x3b808081, v205
	v_fmamk_f32 v2, v2, 0x3b808081, v205
	v_max_f32_e32 v56, 1.0, v56
	v_rcp_f32_e32 v10, v10
	v_rcp_f32_e32 v2, v2
	v_max_f32_e32 v120, 1.0, v120
	v_max_f32_e32 v112, 1.0, v112
	v_max_f32_e32 v104, 1.0, v104
	v_max_f32_e32 v96, 1.0, v96
	v_max_f32_e32 v88, 1.0, v88
	v_max_f32_e32 v80, 1.0, v80
	v_max_f32_e32 v72, 1.0, v72
	v_max_f32_e32 v64, 1.0, v64
	v_fmamk_f32 v60, v60, 0xbfb8aa3b, v170
	v_rndne_f32_e32 v56, v56
	v_max_f32_e32 v57, 1.0, v57
	v_max_f32_e32 v48, 1.0, v48
	v_max_f32_e32 v40, 1.0, v40
	v_max_f32_e32 v32, 1.0, v32
	v_max_f32_e32 v24, 1.0, v24
	v_max_f32_e32 v16, 1.0, v16
	v_max_f32_e32 v8, 1.0, v8
	v_max_f32_e32 v0, 1.0, v0
	v_fmamk_f32 v124, v124, 0xbfb8aa3b, v170
	v_rndne_f32_e32 v120, v120
	v_max_f32_e32 v121, 1.0, v121
	v_fmamk_f32 v116, v116, 0xbfb8aa3b, v162
	v_rndne_f32_e32 v112, v112
	v_max_f32_e32 v113, 1.0, v113
	v_fmamk_f32 v108, v108, 0xbfb8aa3b, v170
	v_rndne_f32_e32 v104, v104
	v_max_f32_e32 v105, 1.0, v105
	v_fmamk_f32 v100, v100, 0xbfb8aa3b, v162
	v_rndne_f32_e32 v96, v96
	v_max_f32_e32 v97, 1.0, v97
	v_fmamk_f32 v92, v92, 0xbfb8aa3b, v170
	v_rndne_f32_e32 v88, v88
	v_max_f32_e32 v89, 1.0, v89
	v_fmamk_f32 v84, v84, 0xbfb8aa3b, v162
	v_rndne_f32_e32 v80, v80
	v_max_f32_e32 v81, 1.0, v81
	v_fmamk_f32 v76, v76, 0xbfb8aa3b, v170
	v_rndne_f32_e32 v72, v72
	v_max_f32_e32 v73, 1.0, v73
	v_fmamk_f32 v68, v68, 0xbfb8aa3b, v162
	v_rndne_f32_e32 v64, v64
	v_max_f32_e32 v65, 1.0, v65
	v_exp_f32_e32 v60, v60
	v_cvt_pk_u8_f32 v56, v56, 0, 0
	v_fmamk_f32 v61, v61, 0xbfb8aa3b, v171
	v_rndne_f32_e32 v57, v57
	v_max_f32_e32 v58, 1.0, v58
	v_fmamk_f32 v52, v52, 0xbfb8aa3b, v162
	v_rndne_f32_e32 v48, v48
	v_max_f32_e32 v49, 1.0, v49
	v_fmamk_f32 v44, v44, 0xbfb8aa3b, v170
	v_rndne_f32_e32 v40, v40
	v_max_f32_e32 v41, 1.0, v41
	v_fmamk_f32 v36, v36, 0xbfb8aa3b, v162
	v_rndne_f32_e32 v32, v32
	v_max_f32_e32 v33, 1.0, v33
	v_fmamk_f32 v28, v28, 0xbfb8aa3b, v170
	v_rndne_f32_e32 v24, v24
	v_max_f32_e32 v25, 1.0, v25
	v_fmamk_f32 v20, v20, 0xbfb8aa3b, v162
	v_rndne_f32_e32 v16, v16
	v_max_f32_e32 v17, 1.0, v17
	v_fmamk_f32 v12, v12, 0xbfb8aa3b, v170
	v_rndne_f32_e32 v8, v8
	v_max_f32_e32 v9, 1.0, v9
	v_fmamk_f32 v4, v4, 0xbfb8aa3b, v162
	v_rndne_f32_e32 v0, v0
	v_max_f32_e32 v1, 1.0, v1
	v_pk_mul_f32 v[158:159], v[158:159], s[96:97] op_sel_hi:[1,0]
	v_exp_f32_e32 v124, v124
	v_cvt_pk_u8_f32 v120, v120, 0, 0
	v_fmamk_f32 v125, v125, 0xbfb8aa3b, v171
	v_rndne_f32_e32 v121, v121
	v_max_f32_e32 v122, 1.0, v122
	v_exp_f32_e32 v116, v116
	v_cvt_pk_u8_f32 v112, v112, 0, 0
	v_fmamk_f32 v117, v117, 0xbfb8aa3b, v163
	v_rndne_f32_e32 v113, v113
	v_max_f32_e32 v114, 1.0, v114
	v_exp_f32_e32 v108, v108
	v_cvt_pk_u8_f32 v104, v104, 0, 0
	v_fmamk_f32 v109, v109, 0xbfb8aa3b, v171
	v_rndne_f32_e32 v105, v105
	v_max_f32_e32 v106, 1.0, v106
	v_exp_f32_e32 v100, v100
	v_cvt_pk_u8_f32 v96, v96, 0, 0
	v_fmamk_f32 v101, v101, 0xbfb8aa3b, v163
	v_rndne_f32_e32 v97, v97
	v_max_f32_e32 v98, 1.0, v98
	v_exp_f32_e32 v92, v92
	v_cvt_pk_u8_f32 v88, v88, 0, 0
	v_fmamk_f32 v93, v93, 0xbfb8aa3b, v171
	v_rndne_f32_e32 v89, v89
	v_max_f32_e32 v90, 1.0, v90
	v_exp_f32_e32 v84, v84
	v_cvt_pk_u8_f32 v80, v80, 0, 0
	v_fmamk_f32 v85, v85, 0xbfb8aa3b, v163
	v_rndne_f32_e32 v81, v81
	v_max_f32_e32 v82, 1.0, v82
	v_exp_f32_e32 v76, v76
	v_cvt_pk_u8_f32 v72, v72, 0, 0
	v_fmamk_f32 v77, v77, 0xbfb8aa3b, v171
	v_rndne_f32_e32 v73, v73
	v_max_f32_e32 v74, 1.0, v74
	v_exp_f32_e32 v68, v68
	v_cvt_pk_u8_f32 v64, v64, 0, 0
	v_fmamk_f32 v69, v69, 0xbfb8aa3b, v163
	v_rndne_f32_e32 v65, v65
	v_max_f32_e32 v66, 1.0, v66
	v_exp_f32_e32 v61, v61
	v_cvt_pk_u8_f32 v56, v57, 1, v56
	v_fmamk_f32 v57, v62, 0xbfb8aa3b, v166
	v_rndne_f32_e32 v58, v58
	v_exp_f32_e32 v52, v52
	v_cvt_pk_u8_f32 v48, v48, 0, 0
	v_fmamk_f32 v53, v53, 0xbfb8aa3b, v163
	v_rndne_f32_e32 v49, v49
	v_max_f32_e32 v50, 1.0, v50
	v_exp_f32_e32 v44, v44
	v_cvt_pk_u8_f32 v40, v40, 0, 0
	v_fmamk_f32 v45, v45, 0xbfb8aa3b, v171
	v_rndne_f32_e32 v41, v41
	v_max_f32_e32 v42, 1.0, v42
	v_exp_f32_e32 v36, v36
	v_cvt_pk_u8_f32 v32, v32, 0, 0
	v_fmamk_f32 v37, v37, 0xbfb8aa3b, v163
	v_rndne_f32_e32 v33, v33
	v_max_f32_e32 v34, 1.0, v34
	v_exp_f32_e32 v28, v28
	v_cvt_pk_u8_f32 v24, v24, 0, 0
	v_fmamk_f32 v29, v29, 0xbfb8aa3b, v171
	v_rndne_f32_e32 v25, v25
	v_max_f32_e32 v26, 1.0, v26
	v_exp_f32_e32 v20, v20
	v_cvt_pk_u8_f32 v16, v16, 0, 0
	v_fmamk_f32 v21, v21, 0xbfb8aa3b, v163
	v_rndne_f32_e32 v17, v17
	v_max_f32_e32 v18, 1.0, v18
	v_exp_f32_e32 v12, v12
	v_cvt_pk_u8_f32 v8, v8, 0, 0
	v_fmac_f32_e32 v171, 0xbfb8aa3b, v13
	v_rndne_f32_e32 v9, v9
	v_exp_f32_e32 v4, v4
	v_cvt_pk_u8_f32 v0, v0, 0, 0
	v_fmac_f32_e32 v163, 0xbfb8aa3b, v5
	v_rndne_f32_e32 v1, v1
	v_exp_f32_e32 v125, v125
	v_cvt_pk_u8_f32 v120, v121, 1, v120
	v_fmamk_f32 v121, v126, 0xbfb8aa3b, v166
	v_rndne_f32_e32 v122, v122
	v_exp_f32_e32 v117, v117
	v_cvt_pk_u8_f32 v112, v113, 1, v112
	v_fmamk_f32 v113, v118, 0xbfb8aa3b, v158
	v_rndne_f32_e32 v114, v114
	v_exp_f32_e32 v109, v109
	v_cvt_pk_u8_f32 v104, v105, 1, v104
	v_fmamk_f32 v105, v110, 0xbfb8aa3b, v166
	v_rndne_f32_e32 v106, v106
	v_exp_f32_e32 v101, v101
	v_cvt_pk_u8_f32 v96, v97, 1, v96
	v_fmamk_f32 v97, v102, 0xbfb8aa3b, v158
	v_rndne_f32_e32 v98, v98
	v_exp_f32_e32 v93, v93
	v_cvt_pk_u8_f32 v88, v89, 1, v88
	v_fmamk_f32 v89, v94, 0xbfb8aa3b, v166
	v_rndne_f32_e32 v90, v90
	v_exp_f32_e32 v85, v85
	v_cvt_pk_u8_f32 v80, v81, 1, v80
	v_fmamk_f32 v81, v86, 0xbfb8aa3b, v158
	v_rndne_f32_e32 v82, v82
	v_exp_f32_e32 v77, v77
	v_cvt_pk_u8_f32 v72, v73, 1, v72
	v_fmamk_f32 v73, v78, 0xbfb8aa3b, v166
	v_rndne_f32_e32 v74, v74
	v_exp_f32_e32 v69, v69
	v_cvt_pk_u8_f32 v64, v65, 1, v64
	v_fmamk_f32 v65, v70, 0xbfb8aa3b, v158
	v_rndne_f32_e32 v66, v66
	v_exp_f32_e32 v57, v57
	v_cvt_pk_u8_f32 v58, v58, 2, v56
	v_fmamk_f32 v56, v63, 0xbfb8aa3b, v167
	v_fmamk_f32 v59, v59, 0xbfb8aa3b, v165
	v_exp_f32_e32 v53, v53
	v_cvt_pk_u8_f32 v48, v49, 1, v48
	v_fmamk_f32 v49, v54, 0xbfb8aa3b, v158
	v_rndne_f32_e32 v50, v50
	v_fmamk_f32 v51, v51, 0xbfb8aa3b, v157
	v_exp_f32_e32 v45, v45
	v_cvt_pk_u8_f32 v40, v41, 1, v40
	v_fmamk_f32 v41, v46, 0xbfb8aa3b, v166
	v_rndne_f32_e32 v42, v42
	v_exp_f32_e32 v37, v37
	v_cvt_pk_u8_f32 v32, v33, 1, v32
	v_fmamk_f32 v33, v38, 0xbfb8aa3b, v158
	v_rndne_f32_e32 v34, v34
	v_exp_f32_e32 v29, v29
	v_cvt_pk_u8_f32 v24, v25, 1, v24
	v_fmamk_f32 v25, v30, 0xbfb8aa3b, v166
	v_rndne_f32_e32 v26, v26
	v_exp_f32_e32 v21, v21
	v_cvt_pk_u8_f32 v16, v17, 1, v16
	v_fmamk_f32 v17, v22, 0xbfb8aa3b, v158
	v_rndne_f32_e32 v18, v18
	v_exp_f32_e32 v13, v171
	v_cvt_pk_u8_f32 v8, v9, 1, v8
	v_fmamk_f32 v9, v14, 0xbfb8aa3b, v166
	v_max_f32_e32 v10, 1.0, v10
	v_exp_f32_e32 v5, v163
	v_cvt_pk_u8_f32 v0, v1, 1, v0
	v_fmamk_f32 v1, v6, 0xbfb8aa3b, v158
	v_max_f32_e32 v2, 1.0, v2
	v_exp_f32_e32 v121, v121
	v_cvt_pk_u8_f32 v122, v122, 2, v120
	v_fmamk_f32 v120, v127, 0xbfb8aa3b, v167
	v_fmamk_f32 v123, v123, 0xbfb8aa3b, v165
	v_exp_f32_e32 v113, v113
	v_cvt_pk_u8_f32 v112, v114, 2, v112
	v_fmamk_f32 v114, v119, 0xbfb8aa3b, v159
	v_fmamk_f32 v115, v115, 0xbfb8aa3b, v157
	v_exp_f32_e32 v105, v105
	v_cvt_pk_u8_f32 v106, v106, 2, v104
	v_fmamk_f32 v104, v111, 0xbfb8aa3b, v167
	v_fmamk_f32 v107, v107, 0xbfb8aa3b, v165
	v_exp_f32_e32 v97, v97
	v_cvt_pk_u8_f32 v96, v98, 2, v96
	v_fmamk_f32 v98, v103, 0xbfb8aa3b, v159
	v_fmamk_f32 v99, v99, 0xbfb8aa3b, v157
	v_exp_f32_e32 v89, v89
	v_cvt_pk_u8_f32 v90, v90, 2, v88
	v_fmamk_f32 v88, v95, 0xbfb8aa3b, v167
	v_fmamk_f32 v91, v91, 0xbfb8aa3b, v165
	v_exp_f32_e32 v81, v81
	v_cvt_pk_u8_f32 v80, v82, 2, v80
	v_fmamk_f32 v82, v87, 0xbfb8aa3b, v159
	v_fmamk_f32 v83, v83, 0xbfb8aa3b, v157
	v_exp_f32_e32 v73, v73
	v_cvt_pk_u8_f32 v74, v74, 2, v72
	v_fmamk_f32 v72, v79, 0xbfb8aa3b, v167
	v_fmamk_f32 v75, v75, 0xbfb8aa3b, v165
	v_exp_f32_e32 v65, v65
	v_cvt_pk_u8_f32 v64, v66, 2, v64
	v_fmamk_f32 v66, v71, 0xbfb8aa3b, v159
	v_fmamk_f32 v67, v67, 0xbfb8aa3b, v157
	v_exp_f32_e32 v56, v56
	v_exp_f32_e32 v59, v59
	v_exp_f32_e32 v49, v49
	v_cvt_pk_u8_f32 v48, v50, 2, v48
	v_fmamk_f32 v50, v55, 0xbfb8aa3b, v159
	v_exp_f32_e32 v51, v51
	v_exp_f32_e32 v41, v41
	v_cvt_pk_u8_f32 v42, v42, 2, v40
	v_fmamk_f32 v40, v47, 0xbfb8aa3b, v167
	v_fmamk_f32 v43, v43, 0xbfb8aa3b, v165
	v_exp_f32_e32 v33, v33
	v_cvt_pk_u8_f32 v32, v34, 2, v32
	v_fmamk_f32 v34, v39, 0xbfb8aa3b, v159
	v_fmamk_f32 v35, v35, 0xbfb8aa3b, v157
	v_exp_f32_e32 v25, v25
	v_cvt_pk_u8_f32 v26, v26, 2, v24
	v_fmamk_f32 v24, v31, 0xbfb8aa3b, v167
	v_fmamk_f32 v27, v27, 0xbfb8aa3b, v165
	v_exp_f32_e32 v17, v17
	v_cvt_pk_u8_f32 v16, v18, 2, v16
	v_fmamk_f32 v18, v23, 0xbfb8aa3b, v159
	v_fmamk_f32 v19, v19, 0xbfb8aa3b, v157
	v_exp_f32_e32 v9, v9
	v_rndne_f32_e32 v10, v10
	v_fmac_f32_e32 v167, 0xbfb8aa3b, v15
	v_fmac_f32_e32 v165, 0xbfb8aa3b, v11
	v_exp_f32_e32 v1, v1
	v_rndne_f32_e32 v2, v2
	v_fmac_f32_e32 v159, 0xbfb8aa3b, v7
	v_fmac_f32_e32 v157, 0xbfb8aa3b, v3
	v_exp_f32_e32 v120, v120
	v_exp_f32_e32 v123, v123
	v_exp_f32_e32 v114, v114
	v_exp_f32_e32 v115, v115
	v_exp_f32_e32 v104, v104
	v_exp_f32_e32 v107, v107
	v_exp_f32_e32 v98, v98
	v_exp_f32_e32 v99, v99
	v_exp_f32_e32 v88, v88
	v_exp_f32_e32 v91, v91
	v_exp_f32_e32 v82, v82
	v_exp_f32_e32 v83, v83
	v_exp_f32_e32 v72, v72
	v_exp_f32_e32 v75, v75
	v_exp_f32_e32 v66, v66
	v_exp_f32_e32 v67, v67
	v_fmamk_f32 v60, v60, 0x3b808081, v205
	v_exp_f32_e32 v50, v50
	v_exp_f32_e32 v40, v40
	v_exp_f32_e32 v43, v43
	v_exp_f32_e32 v34, v34
	v_exp_f32_e32 v35, v35
	v_exp_f32_e32 v24, v24
	v_exp_f32_e32 v27, v27
	v_exp_f32_e32 v18, v18
	v_exp_f32_e32 v19, v19
	v_cvt_pk_u8_f32 v10, v10, 2, v8
	v_exp_f32_e32 v8, v167
	v_exp_f32_e32 v11, v165
	v_cvt_pk_u8_f32 v0, v2, 2, v0
	v_exp_f32_e32 v2, v159
	v_exp_f32_e32 v3, v157
	v_fmamk_f32 v124, v124, 0x3b808081, v205
	v_fmamk_f32 v116, v116, 0x3b808081, v205
	v_fmamk_f32 v108, v108, 0x3b808081, v205
	v_fmamk_f32 v100, v100, 0x3b808081, v205
	v_fmamk_f32 v92, v92, 0x3b808081, v205
	v_fmamk_f32 v84, v84, 0x3b808081, v205
	v_fmamk_f32 v76, v76, 0x3b808081, v205
	v_fmamk_f32 v68, v68, 0x3b808081, v205
	v_rcp_f32_e32 v60, v60
	v_fmamk_f32 v61, v61, 0x3b808081, v205
	v_fmamk_f32 v52, v52, 0x3b808081, v205
	v_fmamk_f32 v44, v44, 0x3b808081, v205
	v_fmamk_f32 v36, v36, 0x3b808081, v205
	v_fmamk_f32 v28, v28, 0x3b808081, v205
	v_fmamk_f32 v20, v20, 0x3b808081, v205
	v_fmamk_f32 v12, v12, 0x3b808081, v205
	v_fmamk_f32 v4, v4, 0x3b808081, v205
	v_rcp_f32_e32 v124, v124
	v_fmamk_f32 v125, v125, 0x3b808081, v205
	v_rcp_f32_e32 v116, v116
	v_fmamk_f32 v117, v117, 0x3b808081, v205
	v_rcp_f32_e32 v108, v108
	v_fmamk_f32 v109, v109, 0x3b808081, v205
	v_rcp_f32_e32 v100, v100
	v_fmamk_f32 v101, v101, 0x3b808081, v205
	v_rcp_f32_e32 v92, v92
	v_fmamk_f32 v93, v93, 0x3b808081, v205
	v_rcp_f32_e32 v84, v84
	v_fmamk_f32 v85, v85, 0x3b808081, v205
	v_rcp_f32_e32 v76, v76
	v_fmamk_f32 v77, v77, 0x3b808081, v205
	v_rcp_f32_e32 v68, v68
	v_fmamk_f32 v69, v69, 0x3b808081, v205
	v_rcp_f32_e32 v61, v61
	v_fmamk_f32 v57, v57, 0x3b808081, v205
	v_rcp_f32_e32 v52, v52
	v_fmamk_f32 v53, v53, 0x3b808081, v205
	v_rcp_f32_e32 v44, v44
	v_fmamk_f32 v45, v45, 0x3b808081, v205
	v_rcp_f32_e32 v36, v36
	v_fmamk_f32 v37, v37, 0x3b808081, v205
	v_rcp_f32_e32 v28, v28
	v_fmamk_f32 v29, v29, 0x3b808081, v205
	v_rcp_f32_e32 v20, v20
	v_fmamk_f32 v21, v21, 0x3b808081, v205
	v_rcp_f32_e32 v12, v12
	v_fmamk_f32 v13, v13, 0x3b808081, v205
	v_rcp_f32_e32 v4, v4
	v_fmamk_f32 v5, v5, 0x3b808081, v205
	v_rcp_f32_e32 v125, v125
	v_fmamk_f32 v121, v121, 0x3b808081, v205
	v_rcp_f32_e32 v117, v117
	v_fmamk_f32 v113, v113, 0x3b808081, v205
	v_rcp_f32_e32 v109, v109
	v_fmamk_f32 v105, v105, 0x3b808081, v205
	v_rcp_f32_e32 v101, v101
	v_fmamk_f32 v97, v97, 0x3b808081, v205
	v_rcp_f32_e32 v93, v93
	v_fmamk_f32 v89, v89, 0x3b808081, v205
	v_rcp_f32_e32 v85, v85
	v_fmamk_f32 v81, v81, 0x3b808081, v205
	v_rcp_f32_e32 v77, v77
	v_fmamk_f32 v73, v73, 0x3b808081, v205
	v_rcp_f32_e32 v69, v69
	v_fmamk_f32 v65, v65, 0x3b808081, v205
	v_rcp_f32_e32 v57, v57
	v_fmamk_f32 v56, v56, 0x3b808081, v205
	v_fmamk_f32 v59, v59, 0x3b808081, v205
	v_rcp_f32_e32 v53, v53
	v_fmamk_f32 v49, v49, 0x3b808081, v205
	v_fmamk_f32 v51, v51, 0x3b808081, v205
	v_rcp_f32_e32 v45, v45
	v_fmamk_f32 v41, v41, 0x3b808081, v205
	v_rcp_f32_e32 v37, v37
	v_fmamk_f32 v33, v33, 0x3b808081, v205
	v_rcp_f32_e32 v29, v29
	v_fmamk_f32 v25, v25, 0x3b808081, v205
	v_rcp_f32_e32 v21, v21
	v_fmamk_f32 v17, v17, 0x3b808081, v205
	v_rcp_f32_e32 v13, v13
	v_fmamk_f32 v9, v9, 0x3b808081, v205
	v_rcp_f32_e32 v5, v5
	v_fmamk_f32 v1, v1, 0x3b808081, v205
	v_rcp_f32_e32 v121, v121
	v_fmamk_f32 v120, v120, 0x3b808081, v205
	v_fmamk_f32 v123, v123, 0x3b808081, v205
	v_rcp_f32_e32 v113, v113
	v_fmamk_f32 v114, v114, 0x3b808081, v205
	v_fmamk_f32 v115, v115, 0x3b808081, v205
	v_rcp_f32_e32 v105, v105
	v_fmamk_f32 v104, v104, 0x3b808081, v205
	v_fmamk_f32 v107, v107, 0x3b808081, v205
	v_rcp_f32_e32 v97, v97
	v_fmamk_f32 v98, v98, 0x3b808081, v205
	v_fmamk_f32 v99, v99, 0x3b808081, v205
	v_rcp_f32_e32 v89, v89
	v_fmamk_f32 v88, v88, 0x3b808081, v205
	v_fmamk_f32 v91, v91, 0x3b808081, v205
	v_rcp_f32_e32 v81, v81
	v_fmamk_f32 v82, v82, 0x3b808081, v205
	v_fmamk_f32 v83, v83, 0x3b808081, v205
	v_rcp_f32_e32 v73, v73
	v_fmamk_f32 v72, v72, 0x3b808081, v205
	v_fmamk_f32 v75, v75, 0x3b808081, v205
	v_rcp_f32_e32 v65, v65
	v_fmamk_f32 v66, v66, 0x3b808081, v205
	v_fmamk_f32 v67, v67, 0x3b808081, v205
	v_rcp_f32_e32 v56, v56
	v_rcp_f32_e32 v59, v59
	v_rcp_f32_e32 v49, v49
	v_fmamk_f32 v50, v50, 0x3b808081, v205
	v_rcp_f32_e32 v51, v51
	v_rcp_f32_e32 v41, v41
	v_fmamk_f32 v40, v40, 0x3b808081, v205
	v_fmamk_f32 v43, v43, 0x3b808081, v205
	v_rcp_f32_e32 v33, v33
	v_fmamk_f32 v34, v34, 0x3b808081, v205
	v_fmamk_f32 v35, v35, 0x3b808081, v205
	v_rcp_f32_e32 v25, v25
	v_fmamk_f32 v24, v24, 0x3b808081, v205
	v_fmamk_f32 v27, v27, 0x3b808081, v205
	v_rcp_f32_e32 v17, v17
	v_fmamk_f32 v18, v18, 0x3b808081, v205
	v_fmamk_f32 v19, v19, 0x3b808081, v205
	v_rcp_f32_e32 v9, v9
	v_fmamk_f32 v8, v8, 0x3b808081, v205
	v_fmamk_f32 v11, v11, 0x3b808081, v205
	v_rcp_f32_e32 v1, v1
	v_fmamk_f32 v2, v2, 0x3b808081, v205
	v_fmamk_f32 v3, v3, 0x3b808081, v205
	v_rcp_f32_e32 v120, v120
	v_rcp_f32_e32 v123, v123
	v_rcp_f32_e32 v114, v114
	v_rcp_f32_e32 v115, v115
	v_rcp_f32_e32 v104, v104
	v_rcp_f32_e32 v107, v107
	v_rcp_f32_e32 v98, v98
	v_rcp_f32_e32 v99, v99
	v_rcp_f32_e32 v88, v88
	v_rcp_f32_e32 v91, v91
	v_rcp_f32_e32 v82, v82
	v_rcp_f32_e32 v83, v83
	v_rcp_f32_e32 v72, v72
	v_rcp_f32_e32 v75, v75
	v_rcp_f32_e32 v66, v66
	v_rcp_f32_e32 v67, v67
	v_max_f32_e32 v60, 1.0, v60
	v_rcp_f32_e32 v50, v50
	v_rcp_f32_e32 v40, v40
	v_rcp_f32_e32 v43, v43
	v_rcp_f32_e32 v34, v34
	v_rcp_f32_e32 v35, v35
	v_rcp_f32_e32 v24, v24
	v_rcp_f32_e32 v27, v27
	v_rcp_f32_e32 v18, v18
	v_rcp_f32_e32 v19, v19
	v_rcp_f32_e32 v8, v8
	v_rcp_f32_e32 v11, v11
	v_rcp_f32_e32 v2, v2
	v_rcp_f32_e32 v3, v3
	v_max_f32_e32 v124, 1.0, v124
	v_max_f32_e32 v116, 1.0, v116
	v_max_f32_e32 v108, 1.0, v108
	v_max_f32_e32 v100, 1.0, v100
	v_max_f32_e32 v92, 1.0, v92
	v_max_f32_e32 v84, 1.0, v84
	v_max_f32_e32 v76, 1.0, v76
	v_max_f32_e32 v68, 1.0, v68
	v_rndne_f32_e32 v60, v60
	v_max_f32_e32 v61, 1.0, v61
	v_max_f32_e32 v52, 1.0, v52
	v_max_f32_e32 v44, 1.0, v44
	v_max_f32_e32 v36, 1.0, v36
	v_max_f32_e32 v28, 1.0, v28
	v_max_f32_e32 v20, 1.0, v20
	v_max_f32_e32 v12, 1.0, v12
	v_max_f32_e32 v4, 1.0, v4
	v_rndne_f32_e32 v124, v124
	v_max_f32_e32 v125, 1.0, v125
	v_rndne_f32_e32 v116, v116
	v_max_f32_e32 v117, 1.0, v117
	v_rndne_f32_e32 v108, v108
	v_max_f32_e32 v109, 1.0, v109
	v_rndne_f32_e32 v100, v100
	v_max_f32_e32 v101, 1.0, v101
	v_rndne_f32_e32 v92, v92
	v_max_f32_e32 v93, 1.0, v93
	v_rndne_f32_e32 v84, v84
	v_max_f32_e32 v85, 1.0, v85
	v_rndne_f32_e32 v76, v76
	v_max_f32_e32 v77, 1.0, v77
	v_rndne_f32_e32 v68, v68
	v_max_f32_e32 v69, 1.0, v69
	v_cvt_pk_u8_f32 v60, v60, 0, 0
	v_rndne_f32_e32 v61, v61
	v_max_f32_e32 v57, 1.0, v57
	v_rndne_f32_e32 v52, v52
	v_max_f32_e32 v53, 1.0, v53
	v_rndne_f32_e32 v44, v44
	v_max_f32_e32 v45, 1.0, v45
	v_rndne_f32_e32 v36, v36
	v_max_f32_e32 v37, 1.0, v37
	v_rndne_f32_e32 v28, v28
	v_max_f32_e32 v29, 1.0, v29
	v_rndne_f32_e32 v20, v20
	v_max_f32_e32 v21, 1.0, v21
	v_rndne_f32_e32 v12, v12
	v_max_f32_e32 v13, 1.0, v13
	v_rndne_f32_e32 v4, v4
	v_max_f32_e32 v5, 1.0, v5
	v_cvt_pk_u8_f32 v124, v124, 0, 0
	v_rndne_f32_e32 v125, v125
	v_max_f32_e32 v121, 1.0, v121
	v_cvt_pk_u8_f32 v116, v116, 0, 0
	v_rndne_f32_e32 v117, v117
	v_max_f32_e32 v113, 1.0, v113
	v_cvt_pk_u8_f32 v108, v108, 0, 0
	v_rndne_f32_e32 v109, v109
	v_max_f32_e32 v105, 1.0, v105
	v_cvt_pk_u8_f32 v100, v100, 0, 0
	v_rndne_f32_e32 v101, v101
	v_max_f32_e32 v97, 1.0, v97
	v_cvt_pk_u8_f32 v92, v92, 0, 0
	v_rndne_f32_e32 v93, v93
	v_max_f32_e32 v89, 1.0, v89
	v_cvt_pk_u8_f32 v84, v84, 0, 0
	v_rndne_f32_e32 v85, v85
	v_max_f32_e32 v81, 1.0, v81
	v_cvt_pk_u8_f32 v76, v76, 0, 0
	v_rndne_f32_e32 v77, v77
	v_max_f32_e32 v73, 1.0, v73
	v_cvt_pk_u8_f32 v68, v68, 0, 0
	v_rndne_f32_e32 v69, v69
	v_max_f32_e32 v65, 1.0, v65
	v_cvt_pk_u8_f32 v60, v61, 1, v60
	v_rndne_f32_e32 v57, v57
	v_max_f32_e32 v56, 1.0, v56
	v_max_f32_e32 v59, 1.0, v59
	v_cvt_pk_u8_f32 v52, v52, 0, 0
	v_rndne_f32_e32 v53, v53
	v_max_f32_e32 v49, 1.0, v49
	v_max_f32_e32 v51, 1.0, v51
	v_cvt_pk_u8_f32 v44, v44, 0, 0
	v_rndne_f32_e32 v45, v45
	v_max_f32_e32 v41, 1.0, v41
	v_cvt_pk_u8_f32 v36, v36, 0, 0
	v_rndne_f32_e32 v37, v37
	v_max_f32_e32 v33, 1.0, v33
	v_cvt_pk_u8_f32 v28, v28, 0, 0
	v_rndne_f32_e32 v29, v29
	v_max_f32_e32 v25, 1.0, v25
	v_cvt_pk_u8_f32 v20, v20, 0, 0
	v_rndne_f32_e32 v21, v21
	v_max_f32_e32 v17, 1.0, v17
	v_cvt_pk_u8_f32 v12, v12, 0, 0
	v_rndne_f32_e32 v13, v13
	v_max_f32_e32 v9, 1.0, v9
	v_cvt_pk_u8_f32 v4, v4, 0, 0
	v_rndne_f32_e32 v5, v5
	v_max_f32_e32 v1, 1.0, v1
	v_lshl_add_u64 v[172:173], v[140:141], 0, s[6:7]
	v_cvt_pk_u8_f32 v124, v125, 1, v124
	v_rndne_f32_e32 v121, v121
	v_max_f32_e32 v120, 1.0, v120
	v_max_f32_e32 v123, 1.0, v123
	v_cvt_pk_u8_f32 v116, v117, 1, v116
	v_rndne_f32_e32 v113, v113
	v_max_f32_e32 v114, 1.0, v114
	v_max_f32_e32 v115, 1.0, v115
	v_cvt_pk_u8_f32 v108, v109, 1, v108
	v_rndne_f32_e32 v105, v105
	v_max_f32_e32 v104, 1.0, v104
	v_max_f32_e32 v107, 1.0, v107
	v_cvt_pk_u8_f32 v100, v101, 1, v100
	v_rndne_f32_e32 v97, v97
	v_max_f32_e32 v98, 1.0, v98
	v_max_f32_e32 v99, 1.0, v99
	v_cvt_pk_u8_f32 v92, v93, 1, v92
	v_rndne_f32_e32 v89, v89
	v_max_f32_e32 v88, 1.0, v88
	v_max_f32_e32 v91, 1.0, v91
	v_cvt_pk_u8_f32 v84, v85, 1, v84
	v_rndne_f32_e32 v81, v81
	v_max_f32_e32 v82, 1.0, v82
	v_max_f32_e32 v83, 1.0, v83
	v_cvt_pk_u8_f32 v76, v77, 1, v76
	v_rndne_f32_e32 v73, v73
	v_max_f32_e32 v72, 1.0, v72
	v_max_f32_e32 v75, 1.0, v75
	v_cvt_pk_u8_f32 v68, v69, 1, v68
	v_rndne_f32_e32 v65, v65
	v_max_f32_e32 v66, 1.0, v66
	v_max_f32_e32 v67, 1.0, v67
	v_cvt_pk_u8_f32 v57, v57, 2, v60
	v_rndne_f32_e32 v56, v56
	v_rndne_f32_e32 v59, v59
	v_cvt_pk_u8_f32 v52, v53, 1, v52
	v_rndne_f32_e32 v49, v49
	v_max_f32_e32 v50, 1.0, v50
	v_rndne_f32_e32 v51, v51
	s_movk_i32 s6, 0x1000
	v_cvt_pk_u8_f32 v44, v45, 1, v44
	v_rndne_f32_e32 v41, v41
	v_max_f32_e32 v40, 1.0, v40
	v_max_f32_e32 v43, 1.0, v43
	v_cvt_pk_u8_f32 v36, v37, 1, v36
	v_rndne_f32_e32 v33, v33
	v_max_f32_e32 v34, 1.0, v34
	v_max_f32_e32 v35, 1.0, v35
	v_cvt_pk_u8_f32 v28, v29, 1, v28
	v_rndne_f32_e32 v25, v25
	v_max_f32_e32 v24, 1.0, v24
	v_max_f32_e32 v27, 1.0, v27
	v_cvt_pk_u8_f32 v20, v21, 1, v20
	v_rndne_f32_e32 v17, v17
	v_max_f32_e32 v18, 1.0, v18
	v_max_f32_e32 v19, 1.0, v19
	v_cvt_pk_u8_f32 v12, v13, 1, v12
	v_rndne_f32_e32 v9, v9
	v_max_f32_e32 v8, 1.0, v8
	v_max_f32_e32 v11, 1.0, v11
	v_cvt_pk_u8_f32 v4, v5, 1, v4
	v_rndne_f32_e32 v1, v1
	v_max_f32_e32 v2, 1.0, v2
	v_max_f32_e32 v3, 1.0, v3
	v_cvt_pk_u8_f32 v121, v121, 2, v124
	v_rndne_f32_e32 v120, v120
	v_rndne_f32_e32 v123, v123
	v_cvt_pk_u8_f32 v113, v113, 2, v116
	v_rndne_f32_e32 v114, v114
	v_rndne_f32_e32 v115, v115
	v_cvt_pk_u8_f32 v105, v105, 2, v108
	v_rndne_f32_e32 v104, v104
	v_rndne_f32_e32 v107, v107
	v_cvt_pk_u8_f32 v97, v97, 2, v100
	v_rndne_f32_e32 v98, v98
	v_rndne_f32_e32 v99, v99
	v_cvt_pk_u8_f32 v89, v89, 2, v92
	v_rndne_f32_e32 v88, v88
	v_rndne_f32_e32 v91, v91
	v_cvt_pk_u8_f32 v81, v81, 2, v84
	v_rndne_f32_e32 v82, v82
	v_rndne_f32_e32 v83, v83
	v_cvt_pk_u8_f32 v73, v73, 2, v76
	v_rndne_f32_e32 v72, v72
	v_rndne_f32_e32 v75, v75
	v_cvt_pk_u8_f32 v65, v65, 2, v68
	v_rndne_f32_e32 v66, v66
	v_rndne_f32_e32 v67, v67
	v_cvt_pk_u8_f32 v56, v56, 3, v57
	v_cvt_pk_u8_f32 v57, v59, 3, v58
	v_cvt_pk_u8_f32 v49, v49, 2, v52
	v_rndne_f32_e32 v50, v50
	v_cvt_pk_u8_f32 v59, v51, 3, v48
	v_add_co_u32_e32 v48, vcc, s6, v172
	v_cvt_pk_u8_f32 v41, v41, 2, v44
	v_rndne_f32_e32 v40, v40
	v_rndne_f32_e32 v43, v43
	v_cvt_pk_u8_f32 v33, v33, 2, v36
	v_rndne_f32_e32 v34, v34
	v_rndne_f32_e32 v35, v35
	v_cvt_pk_u8_f32 v25, v25, 2, v28
	v_rndne_f32_e32 v24, v24
	v_rndne_f32_e32 v27, v27
	v_cvt_pk_u8_f32 v17, v17, 2, v20
	v_rndne_f32_e32 v18, v18
	v_rndne_f32_e32 v19, v19
	v_cvt_pk_u8_f32 v9, v9, 2, v12
	v_rndne_f32_e32 v8, v8
	v_rndne_f32_e32 v11, v11
	v_cvt_pk_u8_f32 v1, v1, 2, v4
	v_rndne_f32_e32 v2, v2
	v_rndne_f32_e32 v3, v3
	v_cvt_pk_u8_f32 v120, v120, 3, v121
	v_cvt_pk_u8_f32 v121, v123, 3, v122
	v_cvt_pk_u8_f32 v122, v114, 3, v113
	v_cvt_pk_u8_f32 v123, v115, 3, v112
	v_cvt_pk_u8_f32 v104, v104, 3, v105
	v_cvt_pk_u8_f32 v105, v107, 3, v106
	v_cvt_pk_u8_f32 v106, v98, 3, v97
	v_cvt_pk_u8_f32 v107, v99, 3, v96
	v_cvt_pk_u8_f32 v88, v88, 3, v89
	v_cvt_pk_u8_f32 v89, v91, 3, v90
	v_cvt_pk_u8_f32 v90, v82, 3, v81
	v_cvt_pk_u8_f32 v91, v83, 3, v80
	v_cvt_pk_u8_f32 v72, v72, 3, v73
	v_cvt_pk_u8_f32 v73, v75, 3, v74
	v_cvt_pk_u8_f32 v74, v66, 3, v65
	v_cvt_pk_u8_f32 v75, v67, 3, v64
	v_cvt_pk_u8_f32 v58, v50, 3, v49
	v_addc_co_u32_e32 v49, vcc, 0, v173, vcc
	v_cvt_pk_u8_f32 v40, v40, 3, v41
	v_cvt_pk_u8_f32 v41, v43, 3, v42
	v_cvt_pk_u8_f32 v42, v34, 3, v33
	v_cvt_pk_u8_f32 v43, v35, 3, v32
	v_cvt_pk_u8_f32 v24, v24, 3, v25
	v_cvt_pk_u8_f32 v25, v27, 3, v26
	v_cvt_pk_u8_f32 v26, v18, 3, v17
	v_cvt_pk_u8_f32 v27, v19, 3, v16
	v_cvt_pk_u8_f32 v8, v8, 3, v9
	v_cvt_pk_u8_f32 v9, v11, 3, v10
	v_cvt_pk_u8_f32 v10, v2, 3, v1
	v_cvt_pk_u8_f32 v11, v3, 3, v0
	global_store_dwordx4 v[172:173], v[120:123], off sc1
	global_store_dwordx4 v[172:173], v[104:107], off offset:1024 sc1
	global_store_dwordx4 v[172:173], v[88:91], off offset:2048 sc1
	global_store_dwordx4 v[172:173], v[72:75], off offset:3072 sc1
	global_store_dwordx4 v[48:49], v[56:59], off sc1
	global_store_dwordx4 v[48:49], v[40:43], off offset:1024 sc1
	global_store_dwordx4 v[48:49], v[24:27], off offset:2048 sc1
	global_store_dwordx4 v[48:49], v[8:11], off offset:3072 sc1
